# B-mixer window masks: wave-uniform FULL/EMPTY/PARTIAL dispatch per tile (skip per-element mask VALU on fully valid / fully masked tiles)
# baseline (speedup 1.0000x reference)
; #define WAIT_BAR(N) asm volatile("s_waitcnt vmcnt(%c0) lgkmcnt(0)\n\ts_barrier"::"n"(N):"memory")
;   #define DMA_K(t,slot) glds16(Kh+(long)(t)*KVBLK*KVP,koff,(unsigned)__builtin_amdgcn_readfirstlane(kdst+(slot)))
;   #define DMA_V(t,slot) do{ glds16(Vh+(long)(t)*KVBLK*KVP,voff,(unsigned)__builtin_amdgcn_readfirstlane(vdst+(slot)*VM)); if(DV==128){ glds16(Vh+(long)(t)*KVBLK*KVP+64,voff,(unsigned)__builtin_amdgcn_readfirstlane(vdst+(slot)*VM+8192)); } }while(0)
;   #define CMASK(P0,P1,t) do{ if(MODE==1){ smask(P0,P1,64*((t)+t0)-q0,qrel,hi); } else { int jb_=(t)-(NT-4); if(jb_>=0)cmask(P0,P1,jb_,qrel,hi);} }while(0)
;   #define CMASK(P0,P1,t) do{}while(0)
; __device__ __forceinline__ void smask(f32x16&p0,f32x16&p1,int kb0,int qrel,int hi){
;   const float NEG=-INFINITY; const int d=qrel-kb0-4*hi;
;   #pragma unroll
;   for(int r=0;r<16;++r){const int off=(r&3)+8*(r>>2); if((unsigned)(d-off)>=128u)p0[r]=NEG; if((unsigned)(d-off-32)>=128u)p1[r]=NEG;}
; }
; template<int THRL,int MODE,int KVP,int DV,bool FAST> __device__ __forceinline__ void attn_unit(int b,int qb,const bf16*Qh,const bf16*__restrict__ Kh0,const bf16*__restrict__ Vh0,bf16*Oh,float sink_l2,const EpiArgs ea,char*shm){
;     ...
;   const unsigned voff=(unsigned)((16*(wid&3)+(lane>>2))*KVP+(wid>>2)*32+(lane&3)*8)*2u;
;   const unsigned kdst=lds0+LDS_K+wid*1024, vdst=lds0+LDS_V+wid*1024;
;     ...
;   const int vb0=(int)(lds0+LDS_V)+((lane>>4)&1)*32+(lane&3)*8+(4*hi+((lane&15)>>2))*64;
;   const char*Kbase=shm+LDS_K; bf16x8 kf[8];
;   const lds_cptr shm3=(lds_cptr)shm; const lds_cptr kp0=shm3+LDS_K+hi*1024+r32*16; const lds_cptr vp0=shm3+LDS_V+((lane>>4)&1)*32+(lane&3)*8+(4*hi+((lane&15)>>2))*64;
;   const int NT=(MODE==1)?((qb>0)?6:4):(q0+QB)/KVBLK;
;   DMA_K(0,0);DMA_V(0,0);DMA_K(1,SLOTB);
;   bf16x8 qr[4];
;   #pragma unroll
;   for(int d0=0;d0<4;++d0)qr[d0]=*reinterpret_cast<const bf16x8*>(&Qw[(long)r32*QP+d0*16+hi*8]);
;   float mhat=0.f,l_reg=0.f;f32x16 o[ND]; _Pragma("unroll") for(int d_=0;d_<ND;++d_)o[d_]=f32x16{};f32x16 negm=f32x16{};asm volatile("":"+v"(negm));
;   const int qrel=wid*QBLK+r32;
;     ...
;   bool resc=false;
;     ...
;   f32x16 pA0,pA1,pB0,pB1;
;   int sl_prev=0,sl_cur=0,sl_next=SLOTB;
;     ...
;   DMA_K(2,2*SLOTB);
;   WAIT_BAR(2+NV);
;   qkt(pA0,pA1,Kbase,qr,negm,r32,hi);asm volatile("s_nop 15\n\ts_nop 7":"+v"(pA0),"+v"(pA1));CMASK(pA0,pA1,0);
.LBB0_397:
	s_and_b64 vcc, exec, s[0:1]
	s_cbranch_vccz .LBB0_332
	v_readfirstlane_b32 s24, v229
	s_lshr_b32 s11, s24, 6
	s_lshl_b32 s0, s11, 5
	s_add_i32 s6, s46, s0
	s_lshl_b64 s[18:19], s[6:7], 10
	s_lshl_b64 s[4:5], s[6:7], 11
	s_add_u32 s4, s44, s4
	s_addc_u32 s5, s45, s5
	s_lshl_b32 s1, s11, 4
	v_add_u32_e32 v183, s1, v194
	v_and_or_b32 v0, s1, 48, v233
	s_lshr_b32 s1, s24, 3
	s_and_b32 s1, s1, 0x1fffffe0
	s_lshl_b32 s25, s11, 10
	s_cmp_lg_u32 0, -1
	v_lshl_add_u32 v0, v0, 7, s1
	s_cselect_b32 s1, 0, 0
	s_add_i32 s25, s25, s1
	v_or_b32_e32 v0, v0, v234
	s_add_i32 s26, s25, 0x6000
	s_mov_b32 s1, m0
	s_mov_b32 m0, s25
	s_nop 0
	global_load_lds_dwordx4 v183, s[12:13]
	s_mov_b32 m0, s1
	v_lshlrev_b32_e32 v184, 1, v0
	s_mov_b32 s1, m0
	s_mov_b32 m0, s26
	s_nop 0
	global_load_lds_dwordx4 v184, s[14:15]
	s_mov_b32 m0, s1
	s_add_u32 s20, s12, 0x4000
	s_addc_u32 s21, s13, 0
	s_add_i32 s1, s25, 0x2000
	s_mov_b32 s22, m0
	s_mov_b32 m0, s1
	s_nop 0
	global_load_lds_dwordx4 v183, s[20:21]
	s_mov_b32 m0, s22
	global_load_dwordx4 v[122:125], v197, s[4:5]
	global_load_dwordx4 v[114:117], v197, s[4:5] offset:32
	global_load_dwordx4 v[106:109], v197, s[4:5] offset:64
	global_load_dwordx4 v[98:101], v197, s[4:5] offset:96
	v_mov_b32_e32 v2, v1
	v_mov_b32_e32 v3, v1
	v_mov_b32_e32 v4, v1
	v_mov_b32_e32 v5, v1
	v_mov_b32_e32 v6, v1
	v_mov_b32_e32 v7, v1
	v_mov_b32_e32 v8, v1
	v_mov_b32_e32 v9, v1
	v_mov_b32_e32 v10, v1
	v_mov_b32_e32 v11, v1
	v_mov_b32_e32 v12, v1
	v_mov_b32_e32 v13, v1
	v_mov_b32_e32 v14, v1
	v_mov_b32_e32 v15, v1
	v_mov_b32_e32 v0, v1
	v_mov_b64_e32 v[16:17], v[14:15]
	s_and_b64 s[4:5], s[16:17], exec
	v_mov_b64_e32 v[14:15], v[12:13]
	v_mov_b64_e32 v[12:13], v[10:11]
	v_mov_b64_e32 v[10:11], v[8:9]
	v_mov_b64_e32 v[8:9], v[6:7]
	v_mov_b64_e32 v[6:7], v[4:5]
	v_mov_b64_e32 v[4:5], v[2:3]
	v_mov_b64_e32 v[2:3], v[0:1]
	s_cselect_b32 s23, 4, 6
	s_add_u32 s4, s12, 0x8000
	s_addc_u32 s5, s13, 0
	s_add_i32 s1, s25, 0x4000
	s_mov_b32 s16, m0
	s_mov_b32 m0, s1
	s_nop 0
	global_load_lds_dwordx4 v183, s[4:5]
	s_mov_b32 m0, s16
	s_waitcnt vmcnt(3) lgkmcnt(0)
	s_barrier
	ds_read_b128 v[34:37], v237
	s_lshl_b32 s1, s10, 6
	s_sub_i32 s5, s1, s43
	v_or_b32_e32 v0, s0, v232
	v_or_b32_e32 v50, s5, v238
	v_or_b32_e32 v51, 8, v50
	v_or_b32_e32 v52, 9, v50
	v_or_b32_e32 v53, 10, v50
	s_add_u32 s16, s12, 0xc000
	s_addc_u32 s17, s13, 0
	v_mov_b32_e32 v182, 0
	s_mov_b32 s27, 5
	s_mov_b32 s4, 0
	s_movk_i32 s22, 0x2000
	s_movk_i32 s28, 0x4000
	s_waitcnt vmcnt(3) lgkmcnt(0)
	v_mfma_f32_32x32x16_bf16 v[18:33], v[34:37], v[122:125], v[2:17]
	ds_read_b128 v[34:37], v237 offset:512
	s_waitcnt lgkmcnt(0)
	v_mfma_f32_32x32x16_bf16 v[2:17], v[34:37], v[122:125], v[2:17]
	ds_read_b128 v[34:37], v237 offset:2048
	s_waitcnt vmcnt(2) lgkmcnt(0)
	v_mfma_f32_32x32x16_bf16 v[18:33], v[34:37], v[114:117], v[18:33]
	ds_read_b128 v[34:37], v237 offset:2560
	ds_read_b128 v[38:41], v237 offset:4608
	ds_read_b128 v[42:45], v237 offset:4096
	s_waitcnt lgkmcnt(2)
	v_mfma_f32_32x32x16_bf16 v[2:17], v[34:37], v[114:117], v[2:17]
	ds_read_b128 v[34:37], v237 offset:6656
	ds_read_b128 v[46:49], v237 offset:6144
	s_waitcnt vmcnt(1) lgkmcnt(2)
	v_mfma_f32_32x32x16_bf16 v[18:33], v[42:45], v[106:109], v[18:33]
	v_readfirstlane_b32 s100, v0
	s_nop 3
	s_sub_i32 s100, s100, s5
	s_mov_b32 s101, 0
	s_add_i32 s100, s100, -63
	s_cmp_lt_u32 s100, 34
	s_cselect_b32 s101, 1, s101
	s_add_i32 s100, s100, 94
	s_cmp_ge_u32 s100, 222
	s_cselect_b32 s101, 2, s101
	s_cmp_lg_u32 s101, 0
	s_cbranch_scc1 .Lbm_s0_alt
	v_sub_u32_e32 v42, v0, v50
	v_cmp_gt_u32_e32 vcc, s35, v42
	v_xad_u32 v43, v50, -1, v0
	v_or_b32_e32 v44, 2, v50
	v_or_b32_e32 v45, 3, v50
	v_mfma_f32_32x32x16_bf16 v[2:17], v[38:41], v[106:109], v[2:17]
	v_add_u32_e32 v39, 0xffffff60, v42
	v_add_u32_e32 v40, 0xffffff60, v43
	v_sub_u32_e32 v41, v0, v44
	v_sub_u32_e32 v44, v0, v45
	v_sub_u32_e32 v45, v0, v51
	v_sub_u32_e32 v51, v0, v52
	v_add_u32_e32 v52, 0xffffff60, v51
	s_waitcnt vmcnt(0) lgkmcnt(0)
	v_mfma_f32_32x32x16_bf16 v[18:33], v[46:49], v[98:101], v[18:33]
	v_add_u32_e32 v47, 0xffffff60, v41
	v_add_u32_e32 v48, 0xffffff60, v44
	v_add_u32_e32 v49, 0xffffff60, v45
	v_sub_u32_e32 v46, v0, v53
	v_or_b32_e32 v38, 11, v50
	v_add_u32_e32 v53, 0xffffff60, v46
	v_sub_u32_e32 v38, v0, v38
	v_mfma_f32_32x32x16_bf16 v[2:17], v[34:37], v[98:101], v[2:17]
	s_nop 15
	s_nop 7
	v_add_u32_e32 v34, 0xffffff60, v38
	s_nop 2
	v_cndmask_b32_e32 v18, v198, v18, vcc
	v_cmp_lt_u32_e32 vcc, s36, v39
	s_waitcnt vmcnt(0) lgkmcnt(0)
	s_barrier
; #define WAIT_BAR(N) asm volatile("s_waitcnt vmcnt(%c0) lgkmcnt(0)\n\ts_barrier"::"n"(N):"memory")
;   #define DMA_K(t,slot) glds16(Kh+(long)(t)*KVBLK*KVP,koff,(unsigned)__builtin_amdgcn_readfirstlane(kdst+(slot)))
;   #define DMA_V(t,slot) do{ glds16(Vh+(long)(t)*KVBLK*KVP,voff,(unsigned)__builtin_amdgcn_readfirstlane(vdst+(slot)*VM)); if(DV==128){ glds16(Vh+(long)(t)*KVBLK*KVP+64,voff,(unsigned)__builtin_amdgcn_readfirstlane(vdst+(slot)*VM+8192)); } }while(0)
;   #define CMASK(P0,P1,t) do{ if(MODE==1){ smask(P0,P1,64*((t)+t0)-q0,qrel,hi); } else { int jb_=(t)-(NT-4); if(jb_>=0)cmask(P0,P1,jb_,qrel,hi);} }while(0)
;   #define ROT() do{sl_prev=sl_cur;sl_cur=sl_next;sl_next=(sl_next==(NSLOT-1)*SLOTB)?0:sl_next+SLOTB;}while(0)
;   #define CMASK(P0,P1,t) do{}while(0)
;   #define CMASK(P0,P1,t) do{ if(MODE==1){ smask(P0,P1,64*((t)+t0)-q0,qrel,hi); } else { int jb_=(t)-(NT-4); if(jb_>=0)cmask(P0,P1,jb_,qrel,hi);} }while(0)
; __device__ __forceinline__ void smask(f32x16&p0,f32x16&p1,int kb0,int qrel,int hi){
;   const float NEG=-INFINITY; const int d=qrel-kb0-4*hi;
;   #pragma unroll
;   for(int r=0;r<16;++r){const int off=(r&3)+8*(r>>2); if((unsigned)(d-off)>=128u)p0[r]=NEG; if((unsigned)(d-off-32)>=128u)p1[r]=NEG;}
; }
; template<int THRL,int MODE,int KVP,int DV,bool FAST> __device__ __forceinline__ void attn_unit(int b,int qb,const bf16*Qh,const bf16*__restrict__ Kh0,const bf16*__restrict__ Vh0,bf16*Oh,float sink_l2,const EpiArgs ea,char*shm){
;     ...
;   qkt(pA0,pA1,Kbase,qr,negm,r32,hi);asm volatile("s_nop 15\n\ts_nop 7":"+v"(pA0),"+v"(pA1));CMASK(pA0,pA1,0);
;   START(pA0,pA1);
;   _Pragma("unroll") for(int r=0;r<16;++r)pA1[r]=__builtin_amdgcn_exp2f(pA1[r]);
;   WAIT_BAR(0);
;   DMA_K(3,0);DMA_V(1,SLOTB);
;   ROT();
;   kload8(kf,kp0+sl_cur);
;   WAIT_BAR(1+NV);
;   const f32x16 zero16=f32x16{};
	s_mov_b32 s5, m0
	s_mov_b32 m0, s25
	s_nop 0
	global_load_lds_dwordx4 v183, s[16:17]
	s_mov_b32 m0, s5
	s_add_u32 s16, s14, 0x4000
	s_addc_u32 s17, s15, 0
	s_nop 3
	v_cndmask_b32_e32 v2, v198, v2, vcc
	v_cmp_gt_u32_e32 vcc, s35, v43
	s_add_i32 s5, s25, 0x8000
	s_mov_b32 s20, m0
	s_mov_b32 m0, s5
	s_nop 0
	global_load_lds_dwordx4 v184, s[16:17]
	s_mov_b32 m0, s20
	ds_read_b128 v[154:157], v237 offset:8192
	ds_read_b128 v[92:95], v237 offset:8704
	ds_read_b128 v[150:153], v237 offset:10240
	ds_read_b128 v[146:149], v237 offset:10752
	ds_read_b128 v[142:145], v237 offset:12288
	ds_read_b128 v[138:141], v237 offset:12800
	ds_read_b128 v[134:137], v237 offset:14336
	ds_read_b128 v[130:133], v237 offset:14848
	v_cndmask_b32_e32 v19, v198, v19, vcc
	v_cmp_lt_u32_e32 vcc, s36, v40
	s_add_i32 s29, s23, -2
	s_add_i32 s0, s0, s43
	v_cndmask_b32_e32 v3, v198, v3, vcc
	v_cmp_gt_u32_e32 vcc, s35, v41
	v_exp_f32_e32 v35, v19
	s_waitcnt vmcnt(2) lgkmcnt(0)
	s_barrier
	v_mov_b32_e32 v19, v182
	v_cndmask_b32_e32 v20, v198, v20, vcc
	v_cmp_lt_u32_e32 vcc, s36, v47
	v_exp_f32_e32 v36, v20
	v_mov_b32_e32 v20, v182
	v_cndmask_b32_e32 v4, v198, v4, vcc
	v_cmp_gt_u32_e32 vcc, s35, v44
	s_nop 1
	v_cndmask_b32_e32 v21, v198, v21, vcc
	v_cmp_lt_u32_e32 vcc, s36, v48
	v_exp_f32_e32 v37, v21
	v_mov_b32_e32 v21, v182
	v_cndmask_b32_e32 v5, v198, v5, vcc
	v_cmp_gt_u32_e32 vcc, s35, v45
	s_nop 1
	v_cndmask_b32_e32 v22, v198, v22, vcc
	v_cmp_lt_u32_e32 vcc, s36, v49
	s_nop 1
	v_cndmask_b32_e32 v6, v198, v6, vcc
	v_cmp_gt_u32_e32 vcc, s35, v51
	v_exp_f32_e32 v51, v3
	v_exp_f32_e32 v54, v6
	v_cndmask_b32_e32 v23, v198, v23, vcc
	v_cmp_lt_u32_e32 vcc, s36, v52
	v_exp_f32_e32 v39, v23
	v_exp_f32_e32 v52, v4
	v_cndmask_b32_e32 v7, v198, v7, vcc
	v_cmp_gt_u32_e32 vcc, s35, v46
	v_exp_f32_e32 v55, v7
	v_mov_b32_e32 v3, v182
	v_cndmask_b32_e32 v24, v198, v24, vcc
	v_cmp_lt_u32_e32 vcc, s36, v53
	v_exp_f32_e32 v40, v24
	v_exp_f32_e32 v53, v5
	v_cndmask_b32_e32 v8, v198, v8, vcc
	v_cmp_gt_u32_e32 vcc, s35, v38
	v_exp_f32_e32 v38, v22
	v_exp_f32_e32 v56, v8
	v_cndmask_b32_e32 v25, v198, v25, vcc
	v_cmp_lt_u32_e32 vcc, s36, v34
	v_or_b32_e32 v34, 16, v50
	v_sub_u32_e32 v34, v0, v34
	v_cndmask_b32_e32 v9, v198, v9, vcc
	v_cmp_gt_u32_e32 vcc, s35, v34
	v_add_u32_e32 v34, 0xffffff60, v34
	v_exp_f32_e32 v41, v25
	v_cndmask_b32_e32 v26, v198, v26, vcc
	v_cmp_lt_u32_e32 vcc, s36, v34
	v_or_b32_e32 v34, 17, v50
	v_sub_u32_e32 v34, v0, v34
	v_cndmask_b32_e32 v10, v198, v10, vcc
	v_cmp_gt_u32_e32 vcc, s35, v34
	v_add_u32_e32 v34, 0xffffff60, v34
	v_exp_f32_e32 v42, v26
	v_cndmask_b32_e32 v27, v198, v27, vcc
	v_cmp_lt_u32_e32 vcc, s36, v34
	v_or_b32_e32 v34, 18, v50
	v_sub_u32_e32 v34, v0, v34
	v_cndmask_b32_e32 v11, v198, v11, vcc
	v_cmp_gt_u32_e32 vcc, s35, v34
	v_add_u32_e32 v34, 0xffffff60, v34
	v_exp_f32_e32 v43, v27
	v_cndmask_b32_e32 v28, v198, v28, vcc
	v_cmp_lt_u32_e32 vcc, s36, v34
	v_or_b32_e32 v34, 19, v50
	v_sub_u32_e32 v34, v0, v34
	v_cndmask_b32_e32 v12, v198, v12, vcc
	v_cmp_gt_u32_e32 vcc, s35, v34
	v_add_u32_e32 v34, 0xffffff60, v34
	v_exp_f32_e32 v44, v28
	v_cndmask_b32_e32 v29, v198, v29, vcc
	v_cmp_lt_u32_e32 vcc, s36, v34
	v_or_b32_e32 v34, 24, v50
	v_sub_u32_e32 v34, v0, v34
	v_cndmask_b32_e32 v13, v198, v13, vcc
	v_cmp_gt_u32_e32 vcc, s35, v34
	v_add_u32_e32 v34, 0xffffff60, v34
	v_exp_f32_e32 v45, v29
	v_cndmask_b32_e32 v30, v198, v30, vcc
	v_cmp_lt_u32_e32 vcc, s36, v34
	v_or_b32_e32 v34, 25, v50
	v_sub_u32_e32 v34, v0, v34
	v_cndmask_b32_e32 v14, v198, v14, vcc
	v_cmp_gt_u32_e32 vcc, s35, v34
	v_add_u32_e32 v34, 0xffffff60, v34
	v_exp_f32_e32 v46, v30
	v_cndmask_b32_e32 v31, v198, v31, vcc
	v_cmp_lt_u32_e32 vcc, s36, v34
	v_or_b32_e32 v34, 26, v50
	v_sub_u32_e32 v34, v0, v34
	v_cndmask_b32_e32 v15, v198, v15, vcc
	v_cmp_gt_u32_e32 vcc, s35, v34
	v_add_u32_e32 v34, 0xffffff60, v34
	v_exp_f32_e32 v47, v31
	v_cndmask_b32_e32 v32, v198, v32, vcc
	v_cmp_lt_u32_e32 vcc, s36, v34
	v_or_b32_e32 v34, 27, v50
	v_sub_u32_e32 v34, v0, v34
	v_cndmask_b32_e32 v16, v198, v16, vcc
	v_cmp_gt_u32_e32 vcc, s35, v34
	v_add_u32_e32 v50, 0xffffff60, v34
	v_exp_f32_e32 v34, v18
	v_cndmask_b32_e32 v33, v198, v33, vcc
	v_cmp_lt_u32_e32 vcc, s36, v50
	v_exp_f32_e32 v48, v32
	v_exp_f32_e32 v49, v33
	v_cndmask_b32_e32 v17, v198, v17, vcc
.Lbm_s0_done:
	v_exp_f32_e32 v50, v2
	v_exp_f32_e32 v57, v9
	v_exp_f32_e32 v58, v10
	v_exp_f32_e32 v59, v11
	v_exp_f32_e32 v60, v12
	v_exp_f32_e32 v61, v13
	v_exp_f32_e32 v62, v14
	v_exp_f32_e32 v63, v15
	v_exp_f32_e32 v64, v16
	v_exp_f32_e32 v65, v17
	v_add_u32_e32 v2, s0, v195
	s_add_u32 s0, s14, 0x8000
	v_subrev_u32_e32 v185, s1, v2
	s_addc_u32 s1, s15, 0
	s_add_u32 s12, s12, 0x14000
	s_addc_u32 s13, s13, 0
	v_mov_b32_e32 v2, 0
	v_mov_b32_e32 v4, v182
	v_mov_b32_e32 v5, v182
	v_mov_b32_e32 v6, v182
	v_mov_b32_e32 v7, v182
	v_mov_b32_e32 v8, v182
	v_mov_b32_e32 v9, v182
	v_mov_b32_e32 v10, v182
	v_mov_b32_e32 v11, v182
	v_mov_b32_e32 v12, v182
	v_mov_b32_e32 v13, v182
	v_mov_b32_e32 v14, v182
	v_mov_b32_e32 v15, v182
	v_mov_b32_e32 v16, v182
	v_mov_b32_e32 v17, v182
	v_mov_b32_e32 v18, 0
	v_mov_b32_e32 v22, v182
	v_mov_b32_e32 v23, v182
	v_mov_b32_e32 v24, v182
	v_mov_b32_e32 v25, v182
	v_mov_b32_e32 v26, v182
	v_mov_b32_e32 v27, v182
	v_mov_b32_e32 v28, v182
	v_mov_b32_e32 v29, v182
	v_mov_b32_e32 v30, v182
	v_mov_b32_e32 v31, v182
	v_mov_b32_e32 v32, v182
	v_mov_b32_e32 v33, v182

; __device__ __forceinline__ void smask(f32x16&p0,f32x16&p1,int kb0,int qrel,int hi){
;   const float NEG=-INFINITY; const int d=qrel-kb0-4*hi;
;   #pragma unroll
;   for(int r=0;r<16;++r){const int off=(r&3)+8*(r>>2); if((unsigned)(d-off)>=128u)p0[r]=NEG; if((unsigned)(d-off-32)>=128u)p1[r]=NEG;}
; }
.LBB0_401:
	v_readfirstlane_b32 s100, v185
	s_nop 3
	s_add_i32 s100, s100, 251
	s_mov_b32 s101, 0
	s_add_i32 s100, s100, -63
	s_cmp_lt_u32 s100, 34
	s_cselect_b32 s101, 1, s101
	s_add_i32 s100, s100, 94
	s_cmp_ge_u32 s100, 222
	s_cselect_b32 s101, 2, s101
	s_cmp_lg_u32 s101, 0
	s_cbranch_scc1 .Lbm_b1_alt
	v_add_u32_e32 v38, 0xfb, v185
	v_cmp_gt_u32_e32 vcc, s35, v38
	v_add_u32_e32 v38, 0x5b, v185
	v_add_u32_e32 v39, 0xf2, v185
	v_cndmask_b32_e32 v58, v198, v66, vcc
	v_cmp_lt_u32_e32 vcc, s36, v38
	v_add_u32_e32 v38, 0xfa, v185
	v_add_u32_e32 v40, 0xf1, v185
	v_cndmask_b32_e32 v59, v198, v82, vcc
	v_cmp_gt_u32_e32 vcc, s35, v38
	v_add_u32_e32 v38, 0x5a, v185
	v_add_u32_e32 v41, 0xf0, v185
	v_cndmask_b32_e32 v61, v198, v67, vcc
	v_cmp_lt_u32_e32 vcc, s36, v38
	v_add_u32_e32 v38, 0xf9, v185
	v_add_u32_e32 v42, 0xeb, v185
	v_cndmask_b32_e32 v82, v198, v83, vcc
	v_cmp_gt_u32_e32 vcc, s35, v38
	v_add_u32_e32 v38, 0x59, v185
	v_add_u32_e32 v43, 0xea, v185
	v_cndmask_b32_e32 v62, v198, v68, vcc
	v_cmp_lt_u32_e32 vcc, s36, v38
	v_add_u32_e32 v38, 0xf8, v185
	v_add_u32_e32 v44, 0xe9, v185
	v_cndmask_b32_e32 v83, v198, v84, vcc
	v_cmp_gt_u32_e32 vcc, s35, v38
	v_add_u32_e32 v38, 0x58, v185
	v_add_u32_e32 v45, 0xe8, v185
	v_cndmask_b32_e32 v63, v198, v69, vcc
	v_cmp_lt_u32_e32 vcc, s36, v38
	v_add_u32_e32 v38, 0xf3, v185
	v_add_u32_e32 v46, 0xe3, v185
	v_cndmask_b32_e32 v84, v198, v85, vcc
	v_cmp_gt_u32_e32 vcc, s35, v38
	v_add_u32_e32 v38, 0x53, v185
	v_add_u32_e32 v47, 0xe2, v185
	v_cndmask_b32_e32 v64, v198, v70, vcc
	v_cmp_lt_u32_e32 vcc, s36, v38
	v_add_u32_e32 v48, 0xe1, v185
	v_add_u32_e32 v49, 0xe0, v185
	v_cndmask_b32_e32 v38, v198, v86, vcc
	v_cmp_gt_u32_e32 vcc, s35, v39
	v_add_u32_e32 v39, 0x52, v185
	s_add_i32 s4, s28, s26
	v_cndmask_b32_e32 v65, v198, v71, vcc
	v_cmp_lt_u32_e32 vcc, s36, v39
	s_mov_b32 s5, m0
	s_mov_b32 m0, s4
	s_nop 0
	global_load_lds_dwordx4 v184, s[0:1]
	s_mov_b32 m0, s5
	s_nop 1
	v_cndmask_b32_e32 v39, v198, v87, vcc
	v_cmp_gt_u32_e32 vcc, s35, v40
	v_add_u32_e32 v40, 0x51, v185
	s_nop 0
	v_cndmask_b32_e32 v66, v198, v72, vcc
	v_cmp_lt_u32_e32 vcc, s36, v40
	s_nop 1
	v_cndmask_b32_e32 v40, v198, v88, vcc
	v_cmp_gt_u32_e32 vcc, s35, v41
	v_add_u32_e32 v41, 0x50, v185
	s_nop 0
	v_cndmask_b32_e32 v67, v198, v73, vcc
	v_cmp_lt_u32_e32 vcc, s36, v41
	s_nop 1
	v_cndmask_b32_e32 v41, v198, v89, vcc
	v_cmp_gt_u32_e32 vcc, s35, v42
	v_add_u32_e32 v42, 0x4b, v185
	s_nop 0
	v_cndmask_b32_e32 v68, v198, v74, vcc
	v_cmp_lt_u32_e32 vcc, s36, v42
	s_nop 1
	v_cndmask_b32_e32 v42, v198, v90, vcc
	v_cmp_gt_u32_e32 vcc, s35, v43
	v_add_u32_e32 v43, 0x4a, v185
	s_nop 0
	v_cndmask_b32_e32 v69, v198, v75, vcc
	v_cmp_lt_u32_e32 vcc, s36, v43
	s_nop 1
	v_cndmask_b32_e32 v43, v198, v91, vcc
	v_cmp_gt_u32_e32 vcc, s35, v44
	v_add_u32_e32 v44, 0x49, v185
	s_nop 0
	v_cndmask_b32_e32 v70, v198, v76, vcc
	v_cmp_lt_u32_e32 vcc, s36, v44
	s_nop 1
	v_cndmask_b32_e32 v44, v198, v92, vcc
	v_cmp_gt_u32_e32 vcc, s35, v45
	v_add_u32_e32 v45, 0x48, v185
	s_nop 0
	v_cndmask_b32_e32 v71, v198, v77, vcc
	v_cmp_lt_u32_e32 vcc, s36, v45
	s_nop 1
	v_cndmask_b32_e32 v45, v198, v93, vcc
	v_cmp_gt_u32_e32 vcc, s35, v46
	v_add_u32_e32 v46, 0x43, v185
	s_nop 0
	v_cndmask_b32_e32 v72, v198, v78, vcc
	v_cmp_lt_u32_e32 vcc, s36, v46
	s_nop 1
	v_cndmask_b32_e32 v46, v198, v94, vcc
	v_cmp_gt_u32_e32 vcc, s35, v47
	v_add_u32_e32 v47, 0x42, v185
	s_nop 0
	v_cndmask_b32_e32 v73, v198, v79, vcc
	v_cmp_lt_u32_e32 vcc, s36, v47
	s_nop 1
	v_cndmask_b32_e32 v47, v198, v95, vcc
	v_cmp_gt_u32_e32 vcc, s35, v48
	v_add_u32_e32 v48, 0x41, v185
	s_nop 0
	v_cndmask_b32_e32 v74, v198, v80, vcc
	v_cmp_lt_u32_e32 vcc, s36, v48
	s_nop 1
	v_cndmask_b32_e32 v48, v198, v96, vcc
	v_cmp_gt_u32_e32 vcc, s35, v49
	v_add_u32_e32 v49, 64, v185
	s_nop 0
	v_cndmask_b32_e32 v75, v198, v81, vcc
	v_cmp_lt_u32_e32 vcc, s36, v49
	s_nop 1
	v_cndmask_b32_e32 v49, v198, v97, vcc
.Lbm_b1_done:
	s_waitcnt lgkmcnt(14)
	v_mfma_f32_32x32x16_bf16 v[18:33], v[126:129], v[170:173], v[18:33]
	v_exp_f32_e32 v60, v58
	v_exp_f32_e32 v61, v61
	v_exp_f32_e32 v62, v62
	v_exp_f32_e32 v63, v63
	s_waitcnt lgkmcnt(12)
	v_mfma_f32_32x32x16_bf16 v[2:17], v[126:129], v[154:157], v[2:17]
	v_exp_f32_e32 v64, v64
	v_exp_f32_e32 v65, v65
	v_exp_f32_e32 v66, v66
	v_exp_f32_e32 v67, v67
	v_add_u32_e32 v58, s28, v237
	ds_read_b128 v[154:157], v58
	ds_read_b128 v[92:95], v58 offset:512
	s_waitcnt lgkmcnt(12)
	v_mfma_f32_32x32x16_bf16 v[18:33], v[118:121], v[166:169], v[18:33]
	v_exp_f32_e32 v68, v68
	v_exp_f32_e32 v69, v69
	v_exp_f32_e32 v70, v70
	v_exp_f32_e32 v71, v71
	ds_read_b128 v[150:153], v58 offset:2048
	ds_read_b128 v[146:149], v58 offset:2560
	s_waitcnt lgkmcnt(12)
	v_mfma_f32_32x32x16_bf16 v[2:17], v[118:121], v[34:37], v[2:17]
	v_exp_f32_e32 v72, v72
	v_exp_f32_e32 v73, v73
	v_exp_f32_e32 v74, v74
	v_exp_f32_e32 v75, v75
	ds_read_b128 v[142:145], v58 offset:4096
	ds_read_b128 v[138:141], v58 offset:4608
	s_waitcnt lgkmcnt(12)
	v_mfma_f32_32x32x16_bf16 v[18:33], v[110:113], v[162:165], v[18:33]
	v_exp_f32_e32 v34, v59
	v_exp_f32_e32 v35, v82
	v_exp_f32_e32 v36, v83
	v_exp_f32_e32 v37, v84
	ds_read_b128 v[134:137], v58 offset:6144
	ds_read_b128 v[130:133], v58 offset:6656
	s_waitcnt lgkmcnt(12)
	v_mfma_f32_32x32x16_bf16 v[2:17], v[110:113], v[158:161], v[2:17]
	v_exp_f32_e32 v38, v38
	v_exp_f32_e32 v39, v39
	v_exp_f32_e32 v40, v40
	v_exp_f32_e32 v41, v41
	s_waitcnt lgkmcnt(10)
	v_mfma_f32_32x32x16_bf16 v[18:33], v[102:105], v[54:57], v[18:33]
	v_exp_f32_e32 v42, v42
	v_exp_f32_e32 v43, v43
	v_exp_f32_e32 v44, v44
	v_exp_f32_e32 v45, v45
	s_waitcnt lgkmcnt(8)
	v_mfma_f32_32x32x16_bf16 v[2:17], v[102:105], v[50:53], v[2:17]
	v_exp_f32_e32 v46, v46
	v_exp_f32_e32 v47, v47
	v_exp_f32_e32 v48, v48
	v_exp_f32_e32 v49, v49
	s_mov_b64 s[4:5], -1
	s_and_b64 vcc, exec, s[14:15]
	s_cbranch_vccz .LBB0_407
	s_add_i32 s4, s27, -4
	s_cmp_ge_u32 s4, s29
	s_mov_b64 s[4:5], -1
	s_cbranch_scc0 .LBB0_404
	s_waitcnt vmcnt(0) lgkmcnt(0)
	s_barrier
	s_mov_b64 s[4:5], 0

; __device__ __forceinline__ void smask(f32x16&p0,f32x16&p1,int kb0,int qrel,int hi){
;   const float NEG=-INFINITY; const int d=qrel-kb0-4*hi;
;   #pragma unroll
;   for(int r=0;r<16;++r){const int off=(r&3)+8*(r>>2); if((unsigned)(d-off)>=128u)p0[r]=NEG; if((unsigned)(d-off-32)>=128u)p1[r]=NEG;}
; }
.LBB0_413:
	v_readfirstlane_b32 s100, v185
	s_nop 3
	s_add_i32 s100, s100, 187
	s_mov_b32 s101, 0
	s_add_i32 s100, s100, -63
	s_cmp_lt_u32 s100, 34
	s_cselect_b32 s101, 1, s101
	s_add_i32 s100, s100, 94
	s_cmp_ge_u32 s100, 222
	s_cselect_b32 s101, 2, s101
	s_cmp_lg_u32 s101, 0
	s_cbranch_scc1 .Lbm_b2p0_alt
	v_add_u32_e32 v34, 0xbb, v185
	v_cmp_gt_u32_e32 vcc, s35, v34
	v_add_u32_e32 v35, 0xba, v185
	v_add_u32_e32 v36, 0xb9, v185
	v_cndmask_b32_e32 v34, v198, v76, vcc
	v_cmp_gt_u32_e32 vcc, s35, v35
	v_add_u32_e32 v37, 0xb8, v185
	v_add_u32_e32 v38, 0xb3, v185
	v_cndmask_b32_e32 v35, v198, v77, vcc
	v_cmp_gt_u32_e32 vcc, s35, v36
	v_add_u32_e32 v39, 0xb2, v185
	v_add_u32_e32 v40, 0xb1, v185
	v_cndmask_b32_e32 v36, v198, v78, vcc
	v_cmp_gt_u32_e32 vcc, s35, v37
	v_add_u32_e32 v41, 0xb0, v185
	v_add_u32_e32 v42, 0xab, v185
	v_cndmask_b32_e32 v37, v198, v79, vcc
	v_cmp_gt_u32_e32 vcc, s35, v38
	v_add_u32_e32 v43, 0xaa, v185
	v_add_u32_e32 v44, 0xa9, v185
	v_cndmask_b32_e32 v38, v198, v80, vcc
	v_cmp_gt_u32_e32 vcc, s35, v39
	v_add_u32_e32 v45, 0xa8, v185
	v_add_u32_e32 v46, 0xa3, v185
	v_cndmask_b32_e32 v39, v198, v81, vcc
	v_cmp_gt_u32_e32 vcc, s35, v40
	v_add_u32_e32 v47, 0xa2, v185
	v_add_u32_e32 v48, 0xa1, v185
	v_cndmask_b32_e32 v40, v198, v82, vcc
	v_cmp_gt_u32_e32 vcc, s35, v41
	v_add_u32_e32 v49, 0xa0, v185
	s_nop 0
	v_cndmask_b32_e32 v41, v198, v83, vcc
	v_cmp_gt_u32_e32 vcc, s35, v42
	s_nop 1
	v_cndmask_b32_e32 v42, v198, v84, vcc
	v_cmp_gt_u32_e32 vcc, s35, v43
	s_nop 1
	v_cndmask_b32_e32 v43, v198, v85, vcc
	v_cmp_gt_u32_e32 vcc, s35, v44
	s_nop 1
	v_cndmask_b32_e32 v44, v198, v86, vcc
	v_cmp_gt_u32_e32 vcc, s35, v45
	s_nop 1
	v_cndmask_b32_e32 v45, v198, v87, vcc
	v_cmp_gt_u32_e32 vcc, s35, v46
	s_nop 1
	v_cndmask_b32_e32 v46, v198, v88, vcc
	v_cmp_gt_u32_e32 vcc, s35, v47
	s_nop 1
	v_cndmask_b32_e32 v47, v198, v89, vcc
	v_cmp_gt_u32_e32 vcc, s35, v48
	s_nop 1
	v_cndmask_b32_e32 v48, v198, v90, vcc
	v_cmp_gt_u32_e32 vcc, s35, v49
	s_nop 1
	v_cndmask_b32_e32 v49, v198, v91, vcc
.Lbm_b2p0_done:
	s_waitcnt lgkmcnt(14)
	v_mfma_f32_32x32x16_bf16 v[18:33], v[126:129], v[178:181], v[18:33]
	v_exp_f32_e32 v34, v34
	v_exp_f32_e32 v35, v35
	v_exp_f32_e32 v36, v36
	v_exp_f32_e32 v37, v37
	s_waitcnt lgkmcnt(12)
	v_mfma_f32_32x32x16_bf16 v[2:17], v[126:129], v[174:177], v[2:17]
	v_exp_f32_e32 v38, v38
	v_exp_f32_e32 v39, v39
	v_exp_f32_e32 v40, v40
	v_exp_f32_e32 v41, v41
	v_cndmask_b32_e64 v75, 0, 1, s[20:21]
	v_cmp_ne_u32_e64 s[4:5], 1, v75
	s_andn2_b64 vcc, exec, s[20:21]
	v_add_u32_e32 v75, s22, v237
	s_cbranch_vccnz .LBB0_415
	ds_read_b128 v[154:157], v75
	ds_read_b128 v[92:95], v75 offset:512

; __device__ __forceinline__ void smask(f32x16&p0,f32x16&p1,int kb0,int qrel,int hi){
;   const float NEG=-INFINITY; const int d=qrel-kb0-4*hi;
;   #pragma unroll
;   for(int r=0;r<16;++r){const int off=(r&3)+8*(r>>2); if((unsigned)(d-off)>=128u)p0[r]=NEG; if((unsigned)(d-off-32)>=128u)p1[r]=NEG;}
; }
.LBB0_419:
	s_cmp_lg_u32 s101, 0
	s_cbranch_scc1 .Lbm_b2p1_alt
	v_add_u32_e32 v76, 27, v185
	v_cmp_lt_u32_e32 vcc, s36, v76
	v_add_u32_e32 v76, 26, v185
	s_waitcnt lgkmcnt(6)
	v_mfma_f32_32x32x16_bf16 v[18:33], v[110:113], v[162:165], v[18:33]
	v_cndmask_b32_e32 v50, v198, v50, vcc
	v_cmp_lt_u32_e32 vcc, s36, v76
	v_add_u32_e32 v76, 25, v185
	v_exp_f32_e32 v50, v50
	v_cndmask_b32_e32 v51, v198, v51, vcc
	v_cmp_lt_u32_e32 vcc, s36, v76
	v_add_u32_e32 v76, 24, v185
	v_exp_f32_e32 v51, v51
	v_cndmask_b32_e32 v52, v198, v52, vcc
	v_cmp_lt_u32_e32 vcc, s36, v76
	v_add_u32_e32 v76, 19, v185
	v_exp_f32_e32 v52, v52
	v_cndmask_b32_e32 v53, v198, v53, vcc
	v_cmp_lt_u32_e32 vcc, s36, v76
	v_add_u32_e32 v76, 18, v185
	v_exp_f32_e32 v53, v53
	v_cndmask_b32_e32 v54, v198, v54, vcc
	v_cmp_lt_u32_e32 vcc, s36, v76
	v_add_u32_e32 v76, 17, v185
	s_nop 0
	v_cndmask_b32_e32 v55, v198, v55, vcc
	v_cmp_lt_u32_e32 vcc, s36, v76
	v_add_u32_e32 v76, 16, v185
	s_nop 0
	v_cndmask_b32_e32 v56, v198, v56, vcc
	v_cmp_lt_u32_e32 vcc, s36, v76
	v_add_u32_e32 v76, 11, v185
	s_nop 0
	v_cndmask_b32_e32 v57, v198, v57, vcc
	v_cmp_lt_u32_e32 vcc, s36, v76
	v_add_u32_e32 v76, 10, v185
	s_nop 0
	v_cndmask_b32_e32 v58, v198, v58, vcc
	v_cmp_lt_u32_e32 vcc, s36, v76
	v_add_u32_e32 v76, 9, v185
	s_nop 0
	v_cndmask_b32_e32 v59, v198, v59, vcc
	v_cmp_lt_u32_e32 vcc, s36, v76
	v_add_u32_e32 v76, 8, v185
	s_nop 0
	v_cndmask_b32_e32 v60, v198, v60, vcc
	v_cmp_lt_u32_e32 vcc, s36, v76
	v_add_u32_e32 v76, 3, v185
	s_nop 0
	v_cndmask_b32_e32 v61, v198, v61, vcc
	v_cmp_lt_u32_e32 vcc, s36, v76
	v_add_u32_e32 v76, 2, v185
	s_nop 0
	v_cndmask_b32_e32 v62, v198, v62, vcc
	v_cmp_lt_u32_e32 vcc, s36, v76
	v_add_u32_e32 v76, 1, v185
	s_nop 0
	v_cndmask_b32_e32 v63, v198, v63, vcc
	v_cmp_lt_u32_e32 vcc, s36, v76
	s_nop 1
	v_cndmask_b32_e32 v64, v198, v64, vcc
	v_cmp_lt_u32_e32 vcc, s36, v185
	s_nop 1
	v_cndmask_b32_e32 v65, v198, v65, vcc
.Lbm_b2p1_done:
	s_and_b64 vcc, exec, s[4:5]
	s_cbranch_vccnz .LBB0_421
	ds_read_b128 v[134:137], v75 offset:6144
	ds_read_b128 v[130:133], v75 offset:6656

; __device__ __forceinline__ void smask(f32x16&p0,f32x16&p1,int kb0,int qrel,int hi){
;   const float NEG=-INFINITY; const int d=qrel-kb0-4*hi;
;   #pragma unroll
;   for(int r=0;r<16;++r){const int off=(r&3)+8*(r>>2); if((unsigned)(d-off)>=128u)p0[r]=NEG; if((unsigned)(d-off-32)>=128u)p1[r]=NEG;}
; }
.LBB0_431:
	s_and_b32 s0, s24, 0x3fffffc0
	s_lshl_b32 s0, s0, 2
	s_add_i32 s4, s0, 0
	s_add_i32 s4, s4, 0x12000
	v_add_u32_e32 v166, s28, v235
	ds_read_b64_tr_b16 v[162:163], v166 offset:24576
	ds_read_b64_tr_b16 v[164:165], v166 offset:25088
	v_add_f32_e32 v66, v34, v35
	v_add_f32_e32 v66, v36, v66
	v_add_f32_e32 v66, v37, v66
	v_add_f32_e32 v66, v38, v66
	v_add_f32_e32 v82, v39, v66
	v_mfma_f32_32x32x16_bf16 v[66:81], v[154:157], v[122:125], 0
	v_cvt_pk_bf16_f32 v126, v34, v35
	v_cvt_pk_bf16_f32 v127, v36, v37
	ds_read_b64_tr_b16 v[158:159], v166 offset:28672
	ds_read_b64_tr_b16 v[160:161], v166 offset:29184
	v_add_f32_e32 v34, v40, v82
	v_add_f32_e32 v34, v41, v34
	v_add_f32_e32 v34, v42, v34
	v_add_f32_e32 v34, v43, v34
	v_cvt_pk_bf16_f32 v128, v38, v39
	v_cvt_pk_bf16_f32 v129, v40, v41
	v_mfma_f32_32x32x16_bf16 v[82:97], v[92:95], v[122:125], 0
	ds_read_b64_tr_b16 v[154:155], v166 offset:25600
	ds_read_b64_tr_b16 v[156:157], v166 offset:26112
	v_mfma_f32_32x32x16_bf16 v[66:81], v[150:153], v[114:117], v[66:81]
	v_add_f32_e32 v34, v44, v34
	v_add_f32_e32 v34, v45, v34
	v_add_f32_e32 v34, v46, v34
	v_add_f32_e32 v38, v47, v34
	v_cvt_pk_bf16_f32 v118, v42, v43
	v_cvt_pk_bf16_f32 v119, v44, v45
	ds_read_b64_tr_b16 v[34:35], v166 offset:29696
	ds_read_b64_tr_b16 v[36:37], v166 offset:30208
	v_add_f32_e32 v38, v48, v38
	v_add_f32_e32 v38, v49, v38
	v_add_f32_e32 v38, v50, v38
	v_add_f32_e32 v38, v51, v38
	v_cvt_pk_bf16_f32 v120, v46, v47
	v_cvt_pk_bf16_f32 v121, v48, v49
	v_mfma_f32_32x32x16_bf16 v[82:97], v[146:149], v[114:117], v[82:97]
	ds_read_b64_tr_b16 v[146:147], v166 offset:26624
	ds_read_b64_tr_b16 v[148:149], v166 offset:27136
	v_mfma_f32_32x32x16_bf16 v[66:81], v[142:145], v[106:109], v[66:81]
	v_add_f32_e32 v38, v52, v38
	v_add_f32_e32 v38, v53, v38
	v_add_f32_e32 v38, v54, v38
	v_add_f32_e32 v38, v55, v38
	v_cvt_pk_bf16_f32 v110, v50, v51
	v_cvt_pk_bf16_f32 v111, v52, v53
	ds_read_b64_tr_b16 v[122:123], v166 offset:30720
	ds_read_b64_tr_b16 v[124:125], v166 offset:31232
	v_add_f32_e32 v38, v56, v38
	v_add_f32_e32 v38, v57, v38
	v_add_f32_e32 v38, v58, v38
	v_add_f32_e32 v38, v59, v38
	v_cvt_pk_bf16_f32 v112, v54, v55
	v_cvt_pk_bf16_f32 v113, v56, v57
	v_mfma_f32_32x32x16_bf16 v[82:97], v[138:141], v[106:109], v[82:97]
	ds_read_b64_tr_b16 v[114:115], v166 offset:27648
	ds_read_b64_tr_b16 v[116:117], v166 offset:28160
	v_mfma_f32_32x32x16_bf16 v[66:81], v[134:137], v[98:101], v[66:81]
	v_add_f32_e32 v38, v60, v38
	v_add_f32_e32 v38, v61, v38
	v_add_f32_e32 v38, v62, v38
	v_add_f32_e32 v38, v63, v38
	v_cvt_pk_bf16_f32 v102, v58, v59
	v_cvt_pk_bf16_f32 v103, v60, v61
	ds_read_b64_tr_b16 v[106:107], v166 offset:31744
	ds_read_b64_tr_b16 v[108:109], v166 offset:32256
	v_add_f32_e32 v38, v64, v38
	v_add_f32_e32 v38, v65, v38
	v_add_f32_e32 v134, 0, v38
	v_cvt_pk_bf16_f32 v104, v62, v63
	v_cvt_pk_bf16_f32 v105, v64, v65
	v_mfma_f32_32x32x16_bf16 v[82:97], v[130:133], v[98:101], v[82:97]
	s_add_i32 s23, s23, s10
	s_lshl_b32 s0, s23, 6
	s_sub_i32 s0, s0, s43
	s_sub_i32 s0, s0, 64
	v_readfirstlane_b32 s100, v0
	s_nop 3
	s_sub_i32 s100, s100, s0
	s_mov_b32 s101, 0
	s_add_i32 s100, s100, -63
	s_cmp_lt_u32 s100, 34
	s_cselect_b32 s101, 1, s101
	s_add_i32 s100, s100, 94
	s_cmp_ge_u32 s100, 222
	s_cselect_b32 s101, 2, s101
	s_cmp_lg_u32 s101, 0
	s_cbranch_scc1 .Lbm_pl_alt
	v_or_b32_e32 v49, s0, v238
	v_sub_u32_e32 v38, v0, v49
	v_cmp_gt_u32_e32 vcc, s35, v38
	v_add_u32_e32 v38, 0xffffff60, v38
	v_or_b32_e32 v39, 9, v49
	v_cndmask_b32_e32 v50, v198, v66, vcc
	v_cmp_lt_u32_e32 vcc, s36, v38
	v_xad_u32 v38, v49, -1, v0
	v_sub_u32_e32 v39, v0, v39
	v_cndmask_b32_e32 v66, v198, v82, vcc
	v_cmp_gt_u32_e32 vcc, s35, v38
	v_add_u32_e32 v38, 0xffffff60, v38
	v_or_b32_e32 v40, 10, v49
	v_cndmask_b32_e32 v51, v198, v67, vcc
	v_cmp_lt_u32_e32 vcc, s36, v38
	v_or_b32_e32 v38, 2, v49
	v_sub_u32_e32 v38, v0, v38
	v_cndmask_b32_e32 v67, v198, v83, vcc
	v_cmp_gt_u32_e32 vcc, s35, v38
	v_add_u32_e32 v38, 0xffffff60, v38
	v_sub_u32_e32 v40, v0, v40
	v_cndmask_b32_e32 v52, v198, v68, vcc
	v_cmp_lt_u32_e32 vcc, s36, v38
	v_or_b32_e32 v38, 3, v49
	v_sub_u32_e32 v38, v0, v38
	v_cndmask_b32_e32 v68, v198, v84, vcc
	v_cmp_gt_u32_e32 vcc, s35, v38
	v_add_u32_e32 v38, 0xffffff60, v38
	v_or_b32_e32 v41, 11, v49
	v_cndmask_b32_e32 v53, v198, v69, vcc
	v_cmp_lt_u32_e32 vcc, s36, v38
	v_or_b32_e32 v38, 8, v49
	v_sub_u32_e32 v38, v0, v38
	v_cndmask_b32_e32 v69, v198, v85, vcc
	v_cmp_gt_u32_e32 vcc, s35, v38
	v_add_u32_e32 v38, 0xffffff60, v38
	v_sub_u32_e32 v41, v0, v41
	v_cndmask_b32_e32 v54, v198, v70, vcc
	v_cmp_lt_u32_e32 vcc, s36, v38
	v_or_b32_e32 v42, 16, v49
	v_sub_u32_e32 v42, v0, v42
	v_cndmask_b32_e32 v38, v198, v86, vcc
	v_cmp_gt_u32_e32 vcc, s35, v39
	v_add_u32_e32 v39, 0xffffff60, v39
	v_or_b32_e32 v43, 17, v49
	v_cndmask_b32_e32 v55, v198, v71, vcc
	v_cmp_lt_u32_e32 vcc, s36, v39
	v_sub_u32_e32 v43, v0, v43
	v_or_b32_e32 v44, 18, v49
	v_cndmask_b32_e32 v39, v198, v87, vcc
	v_cmp_gt_u32_e32 vcc, s35, v40
	v_add_u32_e32 v40, 0xffffff60, v40
	v_sub_u32_e32 v44, v0, v44
	v_cndmask_b32_e32 v56, v198, v72, vcc
	v_cmp_lt_u32_e32 vcc, s36, v40
	v_or_b32_e32 v45, 19, v49
	v_sub_u32_e32 v45, v0, v45
	v_cndmask_b32_e32 v40, v198, v88, vcc
	v_cmp_gt_u32_e32 vcc, s35, v41
	v_add_u32_e32 v41, 0xffffff60, v41
	v_or_b32_e32 v46, 24, v49
	v_cndmask_b32_e32 v57, v198, v73, vcc
	v_cmp_lt_u32_e32 vcc, s36, v41
	v_sub_u32_e32 v46, v0, v46
	v_or_b32_e32 v47, 25, v49
	v_cndmask_b32_e32 v41, v198, v89, vcc
	v_cmp_gt_u32_e32 vcc, s35, v42
	v_add_u32_e32 v42, 0xffffff60, v42
	v_sub_u32_e32 v47, v0, v47
	v_cndmask_b32_e32 v58, v198, v74, vcc
	v_cmp_lt_u32_e32 vcc, s36, v42
; __device__ __forceinline__ void smask(f32x16&p0,f32x16&p1,int kb0,int qrel,int hi){
;   const float NEG=-INFINITY; const int d=qrel-kb0-4*hi;
;   #pragma unroll
;   for(int r=0;r<16;++r){const int off=(r&3)+8*(r>>2); if((unsigned)(d-off)>=128u)p0[r]=NEG; if((unsigned)(d-off-32)>=128u)p1[r]=NEG;}
; }
	v_or_b32_e32 v48, 26, v49
	v_sub_u32_e32 v48, v0, v48
	v_cndmask_b32_e32 v42, v198, v90, vcc
	v_cmp_gt_u32_e32 vcc, s35, v43
	v_add_u32_e32 v43, 0xffffff60, v43
	v_or_b32_e32 v49, 27, v49
	v_cndmask_b32_e32 v59, v198, v75, vcc
	v_cmp_lt_u32_e32 vcc, s36, v43
	v_sub_u32_e32 v0, v0, v49
	s_nop 0
	v_cndmask_b32_e32 v43, v198, v91, vcc
	v_cmp_gt_u32_e32 vcc, s35, v44
	v_add_u32_e32 v44, 0xffffff60, v44
	s_nop 0
	v_cndmask_b32_e32 v60, v198, v76, vcc
	v_cmp_lt_u32_e32 vcc, s36, v44
	s_nop 1
	v_cndmask_b32_e32 v44, v198, v92, vcc
	v_cmp_gt_u32_e32 vcc, s35, v45
	v_add_u32_e32 v45, 0xffffff60, v45
	s_nop 0
	v_cndmask_b32_e32 v61, v198, v77, vcc
	v_cmp_lt_u32_e32 vcc, s36, v45
	s_nop 1
	v_cndmask_b32_e32 v45, v198, v93, vcc
	v_cmp_gt_u32_e32 vcc, s35, v46
	v_add_u32_e32 v46, 0xffffff60, v46
	s_nop 0
	v_cndmask_b32_e32 v62, v198, v78, vcc
	v_cmp_lt_u32_e32 vcc, s36, v46
	s_nop 1
	v_cndmask_b32_e32 v46, v198, v94, vcc
	v_cmp_gt_u32_e32 vcc, s35, v47
	v_add_u32_e32 v47, 0xffffff60, v47
	s_nop 0
	v_cndmask_b32_e32 v63, v198, v79, vcc
	v_cmp_lt_u32_e32 vcc, s36, v47
	s_nop 1
	v_cndmask_b32_e32 v47, v198, v95, vcc
	v_cmp_gt_u32_e32 vcc, s35, v48
	v_add_u32_e32 v48, 0xffffff60, v48
	s_nop 0
	v_cndmask_b32_e32 v64, v198, v80, vcc
	v_cmp_lt_u32_e32 vcc, s36, v48
	s_nop 1
	v_cndmask_b32_e32 v48, v198, v96, vcc
	v_cmp_gt_u32_e32 vcc, s35, v0
	v_add_u32_e32 v0, 0xffffff60, v0
	s_nop 0
	v_cndmask_b32_e32 v65, v198, v81, vcc
	v_cmp_lt_u32_e32 vcc, s36, v0
	s_nop 1
	v_cndmask_b32_e32 v49, v198, v97, vcc
; #define SBAR() __builtin_amdgcn_sched_barrier(0)
;   #define RESC() do{ if(!FAST&&resc){ asm volatile("s_waitcnt lgkmcnt(0)":::"memory"); \
;       _Pragma("unroll") for(int d_=0;d_<ND;++d_) _Pragma("unroll") for(int r=0;r<16;++r)o[d_][r]*=wsf[crow(r,hi)]; } }while(0)
;   #define PKW(P,B) cvtpk_s(P[B],P[B+1])
; template<int THRL,int MODE,int KVP,int DV,bool FAST> __device__ __forceinline__ void attn_unit(int b,int qb,const bf16*Qh,const bf16*__restrict__ Kh0,const bf16*__restrict__ Vh0,bf16*Oh,float sink_l2,const EpiArgs ea,char*shm){
;     ...
;   STEP(pB0,pB1,pA0,pA1,NT-1,false,false,false); RESC();
;   { float sacc=pB0[0]+pB0[1]; _Pragma("unroll") for(int r=2;r<16;++r)sacc+=pB0[r]; _Pragma("unroll") for(int r=0;r<16;++r)sacc+=pB1[r]; l_reg+=sacc;
;     pw0=(u32x4){PKW(pB0,0),PKW(pB0,2),PKW(pB0,4),PKW(pB0,6)};pw1=(u32x4){PKW(pB0,8),PKW(pB0,10),PKW(pB0,12),PKW(pB0,14)};pw2=(u32x4){PKW(pB1,0),PKW(pB1,2),PKW(pB1,4),PKW(pB1,6)};pw3=(u32x4){PKW(pB1,8),PKW(pB1,10),PKW(pB1,12),PKW(pB1,14)};
;     SBAR(); pv<ND>(o,vb0+sl_cur*VM,PAF(0),PAF(1),PAF(2),PAF(3)); }
;     ...
;   int le=lane; asm volatile("":"+v"(le));
;   const long wrow=rowbase+q0+wid*QBLK;
;   u32x4 gp[DV/16], v1p[DV/16];
;   if(DV==64){ if(ea.epi==2){ const bf16*Gw=ea.Gh+wrow*1024;
;       #pragma unroll
;       for(int i=0;i<4;++i){const int row=i*8+(le>>3),ch=le&7; gp[i]=*(const u32x4*)(Gw+(long)row*1024+ch*8);} } }
;   else { if(ea.epi==1){ const bf16*Gw=ea.Gh+wrow*1024; const bf16*O1w=Oh+wrow*OP; const int ch=le&15;
;       #pragma unroll
;       for(int i=0;i<8;++i){const int row=i*4+(le>>4); v1p[i]=*(const u32x4*)(O1w+(long)row*OP+ch*8); gp[i]=*(const u32x4*)(Gw+(long)row*1024+ch*8);} } }
;   {auto rr=__builtin_amdgcn_permlane32_swap(__float_as_uint(l_reg),__float_as_uint(l_reg),false,false);l_reg=__uint_as_float(rr[0])+__uint_as_float(rr[1]);}
;   if(MODE==1)l_reg+=__builtin_amdgcn_exp2f(sink_l2-mhat);
;   if(hi==0)wsf[32+r32]=l_reg;asm volatile("s_waitcnt lgkmcnt(0)":::"memory");
.Lbm_pl_done:
	s_waitcnt lgkmcnt(14)
	v_mfma_f32_32x32x16_bf16 v[18:33], v[126:129], v[162:165], v[18:33]
	v_exp_f32_e32 v50, v50
	v_exp_f32_e32 v51, v51
	v_exp_f32_e32 v52, v52
	v_exp_f32_e32 v53, v53
	s_waitcnt lgkmcnt(12)
	v_mfma_f32_32x32x16_bf16 v[2:17], v[126:129], v[158:161], v[2:17]
	v_exp_f32_e32 v54, v54
	v_exp_f32_e32 v55, v55
	v_exp_f32_e32 v56, v56
	v_exp_f32_e32 v57, v57
	s_waitcnt lgkmcnt(10)
	v_mfma_f32_32x32x16_bf16 v[18:33], v[118:121], v[154:157], v[18:33]
	v_exp_f32_e32 v58, v58
	v_exp_f32_e32 v59, v59
	v_exp_f32_e32 v60, v60
	v_exp_f32_e32 v61, v61
	s_waitcnt lgkmcnt(8)
	v_mfma_f32_32x32x16_bf16 v[2:17], v[118:121], v[34:37], v[2:17]
	v_exp_f32_e32 v62, v62
	v_exp_f32_e32 v63, v63
	v_exp_f32_e32 v64, v64
	v_exp_f32_e32 v65, v65
	s_waitcnt lgkmcnt(6)
	v_mfma_f32_32x32x16_bf16 v[18:33], v[110:113], v[146:149], v[18:33]
	v_exp_f32_e32 v34, v66
	v_exp_f32_e32 v35, v67
	v_exp_f32_e32 v36, v68
	v_exp_f32_e32 v37, v69
	s_waitcnt lgkmcnt(4)
	v_mfma_f32_32x32x16_bf16 v[2:17], v[110:113], v[122:125], v[2:17]
	v_exp_f32_e32 v38, v38
	v_exp_f32_e32 v39, v39
	v_exp_f32_e32 v40, v40
	v_exp_f32_e32 v41, v41
	s_waitcnt lgkmcnt(2)
	v_mfma_f32_32x32x16_bf16 v[18:33], v[102:105], v[114:117], v[18:33]
	v_exp_f32_e32 v42, v42
	v_exp_f32_e32 v43, v43
	v_exp_f32_e32 v44, v44
	v_exp_f32_e32 v45, v45
	s_waitcnt lgkmcnt(0)
	v_mfma_f32_32x32x16_bf16 v[2:17], v[102:105], v[106:109], v[2:17]
	v_exp_f32_e32 v46, v46
	v_exp_f32_e32 v47, v47
	v_exp_f32_e32 v48, v48
	v_exp_f32_e32 v49, v49
	v_add_f32_e32 v0, v50, v51
	v_add_f32_e32 v0, v52, v0
	v_add_f32_e32 v0, v53, v0
	v_add_f32_e32 v0, v54, v0
	v_add_f32_e32 v0, v55, v0
	v_add_f32_e32 v0, v56, v0
	v_add_f32_e32 v0, v57, v0
	v_add_f32_e32 v0, v58, v0
	v_add_f32_e32 v0, v59, v0
	v_add_f32_e32 v0, v60, v0
	v_add_f32_e32 v0, v61, v0
	v_add_f32_e32 v0, v62, v0
	v_add_f32_e32 v0, v63, v0
	v_add_f32_e32 v0, v64, v0
	v_add_f32_e32 v0, v65, v0
	v_add_f32_e32 v0, v34, v0
	v_add_f32_e32 v0, v35, v0
	v_add_f32_e32 v0, v36, v0
	v_add_f32_e32 v0, v37, v0
	v_add_f32_e32 v0, v38, v0
	v_add_f32_e32 v0, v39, v0
	v_add_f32_e32 v0, v40, v0
	v_add_f32_e32 v0, v41, v0
	v_add_f32_e32 v0, v42, v0
	v_add_f32_e32 v0, v43, v0
	v_add_f32_e32 v0, v44, v0
	v_add_f32_e32 v0, v45, v0
	v_add_f32_e32 v0, v46, v0
	v_add_f32_e32 v0, v47, v0
	v_add_f32_e32 v0, v48, v0
	v_add_f32_e32 v0, v49, v0
	v_add_f32_e32 v66, v182, v134
	v_add_f32_e32 v66, v66, v0
	v_cvt_pk_bf16_f32 v50, v50, v51
	v_cvt_pk_bf16_f32 v51, v52, v53
	v_cvt_pk_bf16_f32 v52, v54, v55
	v_cvt_pk_bf16_f32 v53, v56, v57
	v_cvt_pk_bf16_f32 v34, v34, v35
	v_cvt_pk_bf16_f32 v35, v36, v37
	v_cvt_pk_bf16_f32 v36, v38, v39
	v_cvt_pk_bf16_f32 v37, v40, v41
	v_cvt_pk_bf16_f32 v68, v58, v59
	v_cvt_pk_bf16_f32 v69, v60, v61
	v_cvt_pk_bf16_f32 v70, v62, v63
	v_cvt_pk_bf16_f32 v71, v64, v65
	v_cvt_pk_bf16_f32 v60, v42, v43
	v_cvt_pk_bf16_f32 v61, v44, v45
	v_cvt_pk_bf16_f32 v62, v46, v47
	v_cvt_pk_bf16_f32 v63, v48, v49
	v_add_u32_e32 v0, s22, v236
	ds_read_b64_tr_b16 v[38:39],v0 offset:0
	ds_read_b64_tr_b16 v[40:41],v0 offset:512
	ds_read_b64_tr_b16 v[42:43],v0 offset:1024
	ds_read_b64_tr_b16 v[44:45],v0 offset:1536
	ds_read_b64_tr_b16 v[46:47],v0 offset:2048
	ds_read_b64_tr_b16 v[48:49],v0 offset:2560
	ds_read_b64_tr_b16 v[54:55],v0 offset:3072
	ds_read_b64_tr_b16 v[56:57],v0 offset:3584
	s_waitcnt lgkmcnt(0)
	s_nop 0
	v_mfma_f32_32x32x16_bf16 v[18:33], v[50:53], v[38:41], v[18:33]
	ds_read_b64_tr_b16 v[38:39],v0 offset:4096
	ds_read_b64_tr_b16 v[40:41],v0 offset:4608
	v_mfma_f32_32x32x16_bf16 v[18:33], v[68:71], v[42:45], v[18:33]
	ds_read_b64_tr_b16 v[42:43],v0 offset:5120
	ds_read_b64_tr_b16 v[44:45],v0 offset:5632
	ds_read_b64_tr_b16 v[72:73],v0 offset:6144
	ds_read_b64_tr_b16 v[74:75],v0 offset:6656
	ds_read_b64_tr_b16 v[76:77],v0 offset:7168
	ds_read_b64_tr_b16 v[78:79],v0 offset:7680
	s_waitcnt lgkmcnt(0)
	v_mfma_f32_32x32x16_bf16 v[18:33], v[34:37], v[46:49], v[18:33]
	v_mfma_f32_32x32x16_bf16 v[18:33], v[60:63], v[54:57], v[18:33]
	v_mfma_f32_32x32x16_bf16 v[2:17], v[50:53], v[38:41], v[2:17]
	v_mov_b32_e32 v58, v231
	s_lshl_b64 s[0:1], s[18:19], 1
	v_ashrrev_i32_e32 v56, 3, v58
	v_lshlrev_b32_e32 v0, 3, v58
	s_add_u32 s0, s41, s0
	v_and_b32_e32 v0, 56, v0
	v_mfma_f32_32x32x16_bf16 v[2:17], v[68:71], v[42:45], v[2:17]
	v_add_u32_e32 v54, 8, v56
	s_addc_u32 s1, s42, s1
	v_lshlrev_b32_e32 v0, 1, v0
	v_ashrrev_i32_e32 v57, 31, v56
	v_ashrrev_i32_e32 v55, 31, v54
	v_lshl_add_u64 v[38:39], s[0:1], 0, v[0:1]
	v_lshlrev_b64 v[40:41], 11, v[56:57]
	v_lshlrev_b64 v[42:43], 11, v[54:55]
	v_lshl_add_u64 v[40:41], v[38:39], 0, v[40:41]
	v_lshl_add_u64 v[50:51], v[38:39], 0, v[42:43]
	v_add_u32_e32 v52, 16, v56
	global_load_dwordx4 v[46:49], v[40:41], off
	global_load_dwordx4 v[42:45], v[50:51], off
	v_ashrrev_i32_e32 v53, 31, v52
	v_add_u32_e32 v50, 24, v56
	v_mfma_f32_32x32x16_bf16 v[2:17], v[34:37], v[72:75], v[2:17]
	v_lshlrev_b64 v[34:35], 11, v[52:53]
	v_ashrrev_i32_e32 v51, 31, v50
	v_lshl_add_u64 v[64:65], v[38:39], 0, v[34:35]
	v_lshlrev_b64 v[34:35], 11, v[50:51]
	v_lshl_add_u64 v[68:69], v[38:39], 0, v[34:35]
	global_load_dwordx4 v[38:41], v[64:65], off
	global_load_dwordx4 v[34:37], v[68:69], off
	v_mov_b32_e32 v59, v66
	v_mfma_f32_32x32x16_bf16 v[2:17], v[60:63], v[76:79], v[2:17]
	s_nop 0
	v_permlane32_swap_b32_e32 v66, v59
	s_and_saveexec_b64 s[0:1], s[88:89]
	s_cbranch_execz .LBB0_331
	v_mul_f32_e32 v60, 0x3fb8aa3b, v199
	v_exp_f32_e32 v60, v60
	v_add_f32_e32 v59, v66, v59
	v_add_f32_e32 v59, v60, v59
	v_lshl_add_u32 v60, v232, 2, s4
	ds_write_b32 v60, v59 offset:128
	s_branch .LBB0_331

; __device__ __forceinline__ void smask(f32x16&p0,f32x16&p1,int kb0,int qrel,int hi){
;   const float NEG=-INFINITY; const int d=qrel-kb0-4*hi;
;   #pragma unroll
;   for(int r=0;r<16;++r){const int off=(r&3)+8*(r>>2); if((unsigned)(d-off)>=128u)p0[r]=NEG; if((unsigned)(d-off-32)>=128u)p1[r]=NEG;}
; }
.Lbm_pl_alt:
	s_cmp_eq_u32 s101, 2
	s_cbranch_scc1 .Lbm_pl_empty
	v_mov_b32_e32 v50, v66
	v_mov_b32_e32 v66, v82
	v_mov_b32_e32 v51, v67
	v_mov_b32_e32 v67, v83
	v_mov_b32_e32 v52, v68
	v_mov_b32_e32 v68, v84
	v_mov_b32_e32 v53, v69
	v_mov_b32_e32 v69, v85
	v_mov_b32_e32 v54, v70
	v_mov_b32_e32 v38, v86
	v_mov_b32_e32 v55, v71
	v_mov_b32_e32 v39, v87
	v_mov_b32_e32 v56, v72
	v_mov_b32_e32 v40, v88
	v_mov_b32_e32 v57, v73
	v_mov_b32_e32 v41, v89
	v_mov_b32_e32 v58, v74
	v_mov_b32_e32 v42, v90
	v_mov_b32_e32 v59, v75
	v_mov_b32_e32 v43, v91
	v_mov_b32_e32 v60, v76
	v_mov_b32_e32 v44, v92
	v_mov_b32_e32 v61, v77
	v_mov_b32_e32 v45, v93
	v_mov_b32_e32 v62, v78
	v_mov_b32_e32 v46, v94
	v_mov_b32_e32 v63, v79
	v_mov_b32_e32 v47, v95
	v_mov_b32_e32 v64, v80
	v_mov_b32_e32 v48, v96
	v_mov_b32_e32 v65, v81
	v_mov_b32_e32 v49, v97
	s_branch .Lbm_pl_done
.Lbm_pl_empty:
	v_mov_b32_e32 v50, v198
	v_mov_b32_e32 v66, v198
	v_mov_b32_e32 v51, v198
	v_mov_b32_e32 v67, v198
	v_mov_b32_e32 v52, v198
	v_mov_b32_e32 v68, v198
	v_mov_b32_e32 v53, v198
	v_mov_b32_e32 v69, v198
	v_mov_b32_e32 v54, v198
	v_mov_b32_e32 v38, v198
	v_mov_b32_e32 v55, v198
	v_mov_b32_e32 v39, v198
	v_mov_b32_e32 v56, v198
	v_mov_b32_e32 v40, v198
	v_mov_b32_e32 v57, v198
	v_mov_b32_e32 v41, v198
	v_mov_b32_e32 v58, v198
	v_mov_b32_e32 v42, v198
	v_mov_b32_e32 v59, v198
	v_mov_b32_e32 v43, v198
	v_mov_b32_e32 v60, v198
	v_mov_b32_e32 v44, v198
	v_mov_b32_e32 v61, v198
	v_mov_b32_e32 v45, v198
	v_mov_b32_e32 v62, v198
	v_mov_b32_e32 v46, v198
	v_mov_b32_e32 v63, v198
	v_mov_b32_e32 v47, v198
	v_mov_b32_e32 v64, v198
	v_mov_b32_e32 v48, v198
	v_mov_b32_e32 v65, v198
	v_mov_b32_e32 v49, v198
	s_branch .Lbm_pl_done
.Lbm_b2p1_alt:
	s_cmp_eq_u32 s101, 2
	s_cbranch_scc1 .Lbm_b2p1_empty
	s_waitcnt lgkmcnt(6)
	v_mfma_f32_32x32x16_bf16 v[18:33], v[110:113], v[162:165], v[18:33]
	v_exp_f32_e32 v50, v50
	v_exp_f32_e32 v51, v51
	v_exp_f32_e32 v52, v52
	v_exp_f32_e32 v53, v53
	s_branch .Lbm_b2p1_done
.Lbm_b2p1_empty:
	s_waitcnt lgkmcnt(6)
	v_mfma_f32_32x32x16_bf16 v[18:33], v[110:113], v[162:165], v[18:33]
	v_mov_b32_e32 v50, v198
	v_exp_f32_e32 v50, v50
	v_mov_b32_e32 v51, v198
	v_exp_f32_e32 v51, v51
	v_mov_b32_e32 v52, v198
	v_exp_f32_e32 v52, v52
	v_mov_b32_e32 v53, v198
	v_exp_f32_e32 v53, v53
	v_mov_b32_e32 v54, v198
	v_mov_b32_e32 v55, v198
	v_mov_b32_e32 v56, v198
	v_mov_b32_e32 v57, v198
	v_mov_b32_e32 v58, v198
	v_mov_b32_e32 v59, v198
	v_mov_b32_e32 v60, v198
	v_mov_b32_e32 v61, v198
	v_mov_b32_e32 v62, v198
	v_mov_b32_e32 v63, v198
	v_mov_b32_e32 v64, v198
	v_mov_b32_e32 v65, v198
	s_branch .Lbm_b2p1_done
.Lbm_b2p0_alt:
	s_cmp_eq_u32 s101, 2
	s_cbranch_scc1 .Lbm_b2p0_empty
	v_mov_b32_e32 v34, v76
	v_mov_b32_e32 v35, v77
	v_mov_b32_e32 v36, v78
	v_mov_b32_e32 v37, v79
	v_mov_b32_e32 v38, v80
	v_mov_b32_e32 v39, v81
	v_mov_b32_e32 v40, v82
	v_mov_b32_e32 v41, v83
	v_mov_b32_e32 v42, v84
	v_mov_b32_e32 v43, v85
	v_mov_b32_e32 v44, v86
	v_mov_b32_e32 v45, v87
	v_mov_b32_e32 v46, v88
	v_mov_b32_e32 v47, v89
	v_mov_b32_e32 v48, v90
	v_mov_b32_e32 v49, v91
	s_branch .Lbm_b2p0_done
.Lbm_b2p0_empty:
	v_mov_b32_e32 v34, v198
	v_mov_b32_e32 v35, v198
	v_mov_b32_e32 v36, v198
	v_mov_b32_e32 v37, v198
	v_mov_b32_e32 v38, v198
	v_mov_b32_e32 v39, v198
	v_mov_b32_e32 v40, v198
	v_mov_b32_e32 v41, v198
	v_mov_b32_e32 v42, v198
	v_mov_b32_e32 v43, v198
	v_mov_b32_e32 v44, v198
	v_mov_b32_e32 v45, v198
	v_mov_b32_e32 v46, v198
	v_mov_b32_e32 v47, v198
	v_mov_b32_e32 v48, v198
	v_mov_b32_e32 v49, v198
	s_branch .Lbm_b2p0_done
.Lbm_b1_alt:
	s_cmp_eq_u32 s101, 2
	s_cbranch_scc1 .Lbm_b1_empty
	v_mov_b32_e32 v58, v66
	v_mov_b32_e32 v59, v82
	v_mov_b32_e32 v61, v67
	v_mov_b32_e32 v82, v83
	v_mov_b32_e32 v62, v68
	v_mov_b32_e32 v83, v84
	v_mov_b32_e32 v63, v69
	v_mov_b32_e32 v84, v85
	v_mov_b32_e32 v64, v70
	v_mov_b32_e32 v38, v86
	s_add_i32 s4, s28, s26
	v_mov_b32_e32 v65, v71
	s_mov_b32 s5, m0
	s_mov_b32 m0, s4
	s_nop 0
	global_load_lds_dwordx4 v184, s[0:1]
	s_mov_b32 m0, s5
	v_mov_b32_e32 v39, v87
	v_mov_b32_e32 v66, v72
	v_mov_b32_e32 v40, v88
	v_mov_b32_e32 v67, v73
	v_mov_b32_e32 v41, v89
	v_mov_b32_e32 v68, v74
	v_mov_b32_e32 v42, v90
	v_mov_b32_e32 v69, v75
	v_mov_b32_e32 v43, v91
	v_mov_b32_e32 v70, v76
	v_mov_b32_e32 v44, v92
	v_mov_b32_e32 v71, v77
	v_mov_b32_e32 v45, v93
	v_mov_b32_e32 v72, v78
	v_mov_b32_e32 v46, v94
	v_mov_b32_e32 v73, v79
	v_mov_b32_e32 v47, v95
	v_mov_b32_e32 v74, v80
	v_mov_b32_e32 v48, v96
	v_mov_b32_e32 v75, v81
	v_mov_b32_e32 v49, v97
	s_branch .Lbm_b1_done
; #define WAIT_BAR(N) asm volatile("s_waitcnt vmcnt(%c0) lgkmcnt(0)\n\ts_barrier"::"n"(N):"memory")
;   #define DMA_K(t,slot) glds16(Kh+(long)(t)*KVBLK*KVP,koff,(unsigned)__builtin_amdgcn_readfirstlane(kdst+(slot)))
;   #define DMA_V(t,slot) do{ glds16(Vh+(long)(t)*KVBLK*KVP,voff,(unsigned)__builtin_amdgcn_readfirstlane(vdst+(slot)*VM)); if(DV==128){ glds16(Vh+(long)(t)*KVBLK*KVP+64,voff,(unsigned)__builtin_amdgcn_readfirstlane(vdst+(slot)*VM+8192)); } }while(0)
;   #define CMASK(P0,P1,t) do{ if(MODE==1){ smask(P0,P1,64*((t)+t0)-q0,qrel,hi); } else { int jb_=(t)-(NT-4); if(jb_>=0)cmask(P0,P1,jb_,qrel,hi);} }while(0)
;   #define ROT() do{sl_prev=sl_cur;sl_cur=sl_next;sl_next=(sl_next==(NSLOT-1)*SLOTB)?0:sl_next+SLOTB;}while(0)
;   #define CMASK(P0,P1,t) do{}while(0)
;   #define CMASK(P0,P1,t) do{ if(MODE==1){ smask(P0,P1,64*((t)+t0)-q0,qrel,hi); } else { int jb_=(t)-(NT-4); if(jb_>=0)cmask(P0,P1,jb_,qrel,hi);} }while(0)
; __device__ __forceinline__ void smask(f32x16&p0,f32x16&p1,int kb0,int qrel,int hi){
;   const float NEG=-INFINITY; const int d=qrel-kb0-4*hi;
;   #pragma unroll
;   for(int r=0;r<16;++r){const int off=(r&3)+8*(r>>2); if((unsigned)(d-off)>=128u)p0[r]=NEG; if((unsigned)(d-off-32)>=128u)p1[r]=NEG;}
; }
; template<int THRL,int MODE,int KVP,int DV,bool FAST> __device__ __forceinline__ void attn_unit(int b,int qb,const bf16*Qh,const bf16*__restrict__ Kh0,const bf16*__restrict__ Vh0,bf16*Oh,float sink_l2,const EpiArgs ea,char*shm){
;     ...
;   qkt(pA0,pA1,Kbase,qr,negm,r32,hi);asm volatile("s_nop 15\n\ts_nop 7":"+v"(pA0),"+v"(pA1));CMASK(pA0,pA1,0);
;   START(pA0,pA1);
;   _Pragma("unroll") for(int r=0;r<16;++r)pA1[r]=__builtin_amdgcn_exp2f(pA1[r]);
;   WAIT_BAR(0);
;   DMA_K(3,0);DMA_V(1,SLOTB);
;   ROT();
;   kload8(kf,kp0+sl_cur);
;   WAIT_BAR(1+NV);
.Lbm_b1_empty:
	v_mov_b32_e32 v58, v198
	v_mov_b32_e32 v59, v198
	v_mov_b32_e32 v61, v198
	v_mov_b32_e32 v82, v198
	v_mov_b32_e32 v62, v198
	v_mov_b32_e32 v83, v198
	v_mov_b32_e32 v63, v198
	v_mov_b32_e32 v84, v198
	v_mov_b32_e32 v64, v198
	v_mov_b32_e32 v38, v198
	s_add_i32 s4, s28, s26
	v_mov_b32_e32 v65, v198
	s_mov_b32 s5, m0
	s_mov_b32 m0, s4
	s_nop 0
	global_load_lds_dwordx4 v184, s[0:1]
	s_mov_b32 m0, s5
	v_mov_b32_e32 v39, v198
	v_mov_b32_e32 v66, v198
	v_mov_b32_e32 v40, v198
	v_mov_b32_e32 v67, v198
	v_mov_b32_e32 v41, v198
	v_mov_b32_e32 v68, v198
	v_mov_b32_e32 v42, v198
	v_mov_b32_e32 v69, v198
	v_mov_b32_e32 v43, v198
	v_mov_b32_e32 v70, v198
	v_mov_b32_e32 v44, v198
	v_mov_b32_e32 v71, v198
	v_mov_b32_e32 v45, v198
	v_mov_b32_e32 v72, v198
	v_mov_b32_e32 v46, v198
	v_mov_b32_e32 v73, v198
	v_mov_b32_e32 v47, v198
	v_mov_b32_e32 v74, v198
	v_mov_b32_e32 v48, v198
	v_mov_b32_e32 v75, v198
	v_mov_b32_e32 v49, v198
	s_branch .Lbm_b1_done
.Lbm_s0_alt:
	s_cmp_eq_u32 s101, 2
	s_cbranch_scc1 .Lbm_s0_empty
	v_mfma_f32_32x32x16_bf16 v[2:17], v[38:41], v[106:109], v[2:17]
	s_waitcnt vmcnt(0) lgkmcnt(0)
	v_mfma_f32_32x32x16_bf16 v[18:33], v[46:49], v[98:101], v[18:33]
	v_mfma_f32_32x32x16_bf16 v[2:17], v[34:37], v[98:101], v[2:17]
	s_nop 15
	s_nop 7
	s_waitcnt vmcnt(0) lgkmcnt(0)
	s_barrier
	s_mov_b32 s5, m0
	s_mov_b32 m0, s25
	s_nop 0
	global_load_lds_dwordx4 v183, s[16:17]
	s_mov_b32 m0, s5
	s_add_u32 s16, s14, 0x4000
	s_addc_u32 s17, s15, 0
	s_add_i32 s5, s25, 0x8000
	s_mov_b32 s20, m0
	s_mov_b32 m0, s5
	s_nop 0
	global_load_lds_dwordx4 v184, s[16:17]
	s_mov_b32 m0, s20
	ds_read_b128 v[154:157], v237 offset:8192
	ds_read_b128 v[92:95], v237 offset:8704
	ds_read_b128 v[150:153], v237 offset:10240
	ds_read_b128 v[146:149], v237 offset:10752
	ds_read_b128 v[142:145], v237 offset:12288
	ds_read_b128 v[138:141], v237 offset:12800
	ds_read_b128 v[134:137], v237 offset:14336
	ds_read_b128 v[130:133], v237 offset:14848
	s_add_i32 s29, s23, -2
	s_add_i32 s0, s0, s43
	v_exp_f32_e32 v35, v19
	s_waitcnt vmcnt(2) lgkmcnt(0)
	s_barrier
	v_mov_b32_e32 v19, v182
	v_exp_f32_e32 v36, v20
	v_mov_b32_e32 v20, v182
	v_exp_f32_e32 v37, v21
	v_mov_b32_e32 v21, v182
	v_exp_f32_e32 v51, v3
	v_exp_f32_e32 v54, v6
	v_exp_f32_e32 v39, v23
	v_exp_f32_e32 v52, v4
	v_exp_f32_e32 v55, v7
	v_mov_b32_e32 v3, v182
	v_exp_f32_e32 v40, v24
	v_exp_f32_e32 v53, v5
	v_exp_f32_e32 v38, v22
	v_exp_f32_e32 v56, v8
	v_exp_f32_e32 v41, v25
	v_exp_f32_e32 v42, v26
	v_exp_f32_e32 v43, v27
	v_exp_f32_e32 v44, v28
	v_exp_f32_e32 v45, v29
	v_exp_f32_e32 v46, v30
	v_exp_f32_e32 v47, v31
	v_exp_f32_e32 v34, v18
	v_exp_f32_e32 v48, v32
	v_exp_f32_e32 v49, v33
	s_branch .Lbm_s0_done
.Lbm_s0_empty:
	v_mfma_f32_32x32x16_bf16 v[2:17], v[38:41], v[106:109], v[2:17]
	s_waitcnt vmcnt(0) lgkmcnt(0)
	v_mfma_f32_32x32x16_bf16 v[18:33], v[46:49], v[98:101], v[18:33]
	v_mfma_f32_32x32x16_bf16 v[2:17], v[34:37], v[98:101], v[2:17]
	s_nop 15
	s_nop 7
	v_mov_b32_e32 v18, v198
	s_waitcnt vmcnt(0) lgkmcnt(0)
	s_barrier
	s_mov_b32 s5, m0
	s_mov_b32 m0, s25
	s_nop 0
	global_load_lds_dwordx4 v183, s[16:17]
	s_mov_b32 m0, s5
	s_add_u32 s16, s14, 0x4000
	s_addc_u32 s17, s15, 0
	v_mov_b32_e32 v2, v198
	s_add_i32 s5, s25, 0x8000
	s_mov_b32 s20, m0
	s_mov_b32 m0, s5
	s_nop 0
	global_load_lds_dwordx4 v184, s[16:17]
	s_mov_b32 m0, s20
	ds_read_b128 v[154:157], v237 offset:8192
	ds_read_b128 v[92:95], v237 offset:8704
	ds_read_b128 v[150:153], v237 offset:10240
	ds_read_b128 v[146:149], v237 offset:10752
	ds_read_b128 v[142:145], v237 offset:12288
	ds_read_b128 v[138:141], v237 offset:12800
	ds_read_b128 v[134:137], v237 offset:14336
	ds_read_b128 v[130:133], v237 offset:14848
	v_mov_b32_e32 v19, v198
	s_add_i32 s29, s23, -2
	s_add_i32 s0, s0, s43
	v_mov_b32_e32 v3, v198
	v_exp_f32_e32 v35, v19
	s_waitcnt vmcnt(2) lgkmcnt(0)
	s_barrier
	v_mov_b32_e32 v19, v182
	v_mov_b32_e32 v20, v198
	v_exp_f32_e32 v36, v20
	v_mov_b32_e32 v20, v182
	v_mov_b32_e32 v4, v198
	v_mov_b32_e32 v21, v198
	v_exp_f32_e32 v37, v21
	v_mov_b32_e32 v21, v182
	v_mov_b32_e32 v5, v198
	v_mov_b32_e32 v22, v198
	v_mov_b32_e32 v6, v198
	v_exp_f32_e32 v51, v3
	v_exp_f32_e32 v54, v6
	v_mov_b32_e32 v23, v198
	v_exp_f32_e32 v39, v23
	v_exp_f32_e32 v52, v4
	v_mov_b32_e32 v7, v198
	v_exp_f32_e32 v55, v7
	v_mov_b32_e32 v3, v182
	v_mov_b32_e32 v24, v198
	v_exp_f32_e32 v40, v24
	v_exp_f32_e32 v53, v5
	v_mov_b32_e32 v8, v198
	v_exp_f32_e32 v38, v22
	v_exp_f32_e32 v56, v8
	v_mov_b32_e32 v25, v198
	v_mov_b32_e32 v9, v198
	v_exp_f32_e32 v41, v25
	v_mov_b32_e32 v26, v198
	v_mov_b32_e32 v10, v198
	v_exp_f32_e32 v42, v26
	v_mov_b32_e32 v27, v198
	v_mov_b32_e32 v11, v198
	v_exp_f32_e32 v43, v27
	v_mov_b32_e32 v28, v198
	v_mov_b32_e32 v12, v198
	v_exp_f32_e32 v44, v28
	v_mov_b32_e32 v29, v198
	v_mov_b32_e32 v13, v198
	v_exp_f32_e32 v45, v29
	v_mov_b32_e32 v30, v198
	v_mov_b32_e32 v14, v198
	v_exp_f32_e32 v46, v30
	v_mov_b32_e32 v31, v198
	v_mov_b32_e32 v15, v198
	v_exp_f32_e32 v47, v31
	v_mov_b32_e32 v32, v198
	v_mov_b32_e32 v16, v198
	v_exp_f32_e32 v34, v18
	v_mov_b32_e32 v33, v198
	v_exp_f32_e32 v48, v32
	v_exp_f32_e32 v49, v33
	v_mov_b32_e32 v17, v198
	s_branch .Lbm_s0_done

; __global__ void __launch_bounds__(NWAVES * 64, 2) mega_fwd(Args a) {
;     extern __shared__ __attribute__((aligned(16))) unsigned char lds[];
	.amdhsa_kernel _Z8mega_fwd4Args
		.amdhsa_group_segment_fixed_size 0
		.amdhsa_private_segment_fixed_size 0
		.amdhsa_kernarg_size 400
		.amdhsa_user_sgpr_count 2
		.amdhsa_user_sgpr_dispatch_ptr 0
		.amdhsa_user_sgpr_queue_ptr 0
		.amdhsa_user_sgpr_kernarg_segment_ptr 1
		.amdhsa_user_sgpr_dispatch_id 0
		.amdhsa_user_sgpr_kernarg_preload_length 0
		.amdhsa_user_sgpr_kernarg_preload_offset 0
		.amdhsa_user_sgpr_private_segment_size 0
		.amdhsa_uses_dynamic_stack 0
		.amdhsa_enable_private_segment 0
		.amdhsa_system_sgpr_workgroup_id_x 1
		.amdhsa_system_sgpr_workgroup_id_y 0
		.amdhsa_system_sgpr_workgroup_id_z 0
		.amdhsa_system_sgpr_workgroup_info 0
		.amdhsa_system_vgpr_workitem_id 2
		.amdhsa_next_free_vgpr 256
		.amdhsa_next_free_sgpr 102
		.amdhsa_accum_offset 256
		.amdhsa_reserve_vcc 1
		.amdhsa_float_round_mode_32 0
		.amdhsa_float_round_mode_16_64 0
		.amdhsa_float_denorm_mode_32 3
		.amdhsa_float_denorm_mode_16_64 3
		.amdhsa_dx10_clamp 1
		.amdhsa_ieee_mode 1
		.amdhsa_fp16_overflow 0
		.amdhsa_tg_split 0
		.amdhsa_exception_fp_ieee_invalid_op 0
		.amdhsa_exception_fp_denorm_src 0
		.amdhsa_exception_fp_ieee_div_zero 0
		.amdhsa_exception_fp_ieee_overflow 0
		.amdhsa_exception_fp_ieee_underflow 0
		.amdhsa_exception_fp_ieee_inexact 0
		.amdhsa_exception_int_div_zero 0
	.end_amdhsa_kernel

; __global__ void __launch_bounds__(NWAVES * 64, 2) mega_fwd(Args a) {
;     extern __shared__ __attribute__((aligned(16))) unsigned char lds[];
amdhsa.kernels:
  - .agpr_count:     0
    .args:
      - .offset:         0
        .size:           144
        .value_kind:     by_value
      - .offset:         144
        .size:           4
        .value_kind:     hidden_block_count_x
      - .offset:         148
        .size:           4
        .value_kind:     hidden_block_count_y
      - .offset:         152
        .size:           4
        .value_kind:     hidden_block_count_z
      - .offset:         156
        .size:           2
        .value_kind:     hidden_group_size_x
      - .offset:         158
        .size:           2
        .value_kind:     hidden_group_size_y
      - .offset:         160
        .size:           2
        .value_kind:     hidden_group_size_z
      - .offset:         162
        .size:           2
        .value_kind:     hidden_remainder_x
      - .offset:         164
        .size:           2
        .value_kind:     hidden_remainder_y
      - .offset:         166
        .size:           2
        .value_kind:     hidden_remainder_z
      - .offset:         184
        .size:           8
        .value_kind:     hidden_global_offset_x
      - .offset:         192
        .size:           8
        .value_kind:     hidden_global_offset_y
      - .offset:         200
        .size:           8
        .value_kind:     hidden_global_offset_z
      - .offset:         208
        .size:           2
        .value_kind:     hidden_grid_dims
      - .offset:         232
        .size:           8
        .value_kind:     hidden_multigrid_sync_arg
      - .offset:         264
        .size:           4
        .value_kind:     hidden_dynamic_lds_size
    .group_segment_fixed_size: 0
    .kernarg_segment_align: 8
    .kernarg_segment_size: 400
    .language:       OpenCL C
    .language_version:
      - 2
      - 0
    .max_flat_workgroup_size: 512
    .name:           _Z8mega_fwd4Args
    .private_segment_fixed_size: 0
    .sgpr_count:     108
    .sgpr_spill_count: 95
    .symbol:         _Z8mega_fwd4Args.kd
    .uniform_work_group_size: 1
    .uses_dynamic_stack: false
    .vgpr_count:     256
    .vgpr_spill_count: 0
    .wavefront_size: 64
